# mixprep short-conv loop: all 13 loads of an item issued up front under tap masks, one wait per item (on v044)
# speedup vs baseline: 1.0034x; 1.0019x over previous
; DI unsigned pk2(float lo, float hi) { f32x2 v = {lo, hi}; return __builtin_bit_cast(unsigned, __builtin_convertvector(v, bf2_t)); }
; DI void unpack8(const u32x4 w, float (&f)[8]) { f[0] = bflo(w.x); f[1] = bfhi(w.x); f[2] = bflo(w.y); f[3] = bfhi(w.y); f[4] = bflo(w.z); f[5] = bfhi(w.z); f[6] = bflo(w.w); f[7] = bfhi(w.w); }
; DI void mixprep_phase(const bf16_t* Hm, const float* convw, bf16_t* DP, bf16_t* CAT, int gtid, int nthr) {
;     ...
;     for (int i2 = gtid; i2 < NIT; i2 += nthr) {
;         {
;             const int m = i2 >> 7, c8 = i2 & 127, t = m & (SEQ - 1), c = c8 * 8;
;             const bf16_t* p = Hm + (size_t)m * MIXIN + c;
;             float gb[8], y[8];
;             { const u32x4 w = *(const u32x4*)(p + 1024); unpack8(w, gb); }
; #pragma unroll
;             for (int k = 0; k < 8; ++k) y[k] = 0.f;
; #pragma unroll
;             for (int j = 0; j < 3; ++j) {
;                 const int tt = t - 2 + j;
;                 if (tt >= 0) {
;                     const bf16_t* q = p - (size_t)(2 - j) * MIXIN; float gc[8], xc[8];
;                     { const u32x4 w = *(const u32x4*)(q + 2048); unpack8(w, gc); } { const u32x4 w = *(const u32x4*)(q + 3072); unpack8(w, xc); }
;                     const f32x4 w0 = *(const f32x4*)(convw + j * CONVW + c), w1 = *(const f32x4*)(convw + j * CONVW + c + 4);
;                     y[0] += w0[0] * (gc[0] * xc[0]); y[1] += w0[1] * (gc[1] * xc[1]); y[2] += w0[2] * (gc[2] * xc[2]); y[3] += w0[3] * (gc[3] * xc[3]);
;                     y[4] += w1[0] * (gc[4] * xc[4]); y[5] += w1[1] * (gc[5] * xc[5]); y[6] += w1[2] * (gc[6] * xc[6]); y[7] += w1[3] * (gc[7] * xc[7]);
;                 }
;             }
;             u32x4 o; o.x = pk2(gb[0] * y[0], gb[1] * y[1]); o.y = pk2(gb[2] * y[2], gb[3] * y[3]); o.z = pk2(gb[4] * y[4], gb[5] * y[5]); o.w = pk2(gb[6] * y[6], gb[7] * y[7]);
;             *(u32x4*)(CAT + (size_t)m * D + POOLW + c) = o;
;         }
.LBB0_141:
	v_ashrrev_i32_e32 v4, 7, v20
	v_ashrrev_i32_e32 v5, 31, v4
	v_and_b32_e32 v8, 0x3f8, v21
	v_lshlrev_b64 v[0:1], 13, v[4:5]
	v_readlane_b32 s4, v253, 0
	v_readlane_b32 s5, v253, 1
	v_readlane_b32 s6, v253, 2
	v_readlane_b32 s7, v253, 3
	v_readlane_b32 s8, v253, 4
	v_readlane_b32 s9, v253, 5
	v_readlane_b32 s10, v253, 6
	v_readlane_b32 s11, v253, 7
	v_lshl_add_u64 v[0:1], s[26:27], 0, v[0:1]
	v_lshlrev_b32_e32 v96, 1, v8
	v_lshl_add_u64 v[6:7], v[0:1], 0, v[96:97]
	v_and_b32_e32 v18, 0xfff, v4
	v_lshlrev_b32_e32 v8, 2, v8
	v_mov_b32_e32 v9, v97
	v_lshl_add_u64 v[8:9], s[6:7], 0, v[8:9]
	global_load_dwordx4 v[40:43], v[6:7], off offset:2048
	v_add_co_u32_e32 v44, vcc, s42, v6
	s_nop 1
	v_addc_co_u32_e32 v45, vcc, 0, v7, vcc
	v_add_co_u32_e32 v54, vcc, 0x2000, v8
	s_nop 1
	v_addc_co_u32_e32 v55, vcc, 0, v9, vcc
	global_load_dwordx4 v[46:49], v[44:45], off
	global_load_dwordx4 v[50:53], v[44:45], off offset:2048
	global_load_dwordx4 v[56:59], v[54:55], off
	global_load_dwordx4 v[60:63], v[54:55], off offset:16
	v_mov_b32_e32 v16, v97
	v_mov_b32_e32 v17, v97
	v_mov_b32_e32 v14, v97
	v_mov_b32_e32 v15, v97
	v_mov_b32_e32 v12, v97
	v_mov_b32_e32 v13, v97
	v_mov_b32_e32 v10, v97
	v_mov_b32_e32 v11, v97
	v_cmp_ne_u32_e32 vcc, 0, v18
	s_and_saveexec_b64 s[20:21], vcc
	global_load_dwordx4 v[64:67], v[6:7], off offset:-4096
	global_load_dwordx4 v[68:71], v[6:7], off offset:-2048
	v_add_co_u32_e32 v72, vcc, s42, v8
	s_nop 1
	v_addc_co_u32_e32 v73, vcc, 0, v9, vcc
	global_load_dwordx4 v[74:77], v[72:73], off
	global_load_dwordx4 v[78:81], v[72:73], off offset:16
	v_cmp_lt_u32_e32 vcc, 1, v18
	s_and_saveexec_b64 s[10:11], vcc
	v_add_co_u32_e32 v82, vcc, 0xffffd000, v6
	s_nop 1
	v_addc_co_u32_e32 v83, vcc, -1, v7, vcc
	v_add_co_u32_e32 v88, vcc, 0xffffe000, v6
	s_nop 1
	v_addc_co_u32_e32 v89, vcc, -1, v7, vcc
	global_load_dwordx4 v[84:87], v[82:83], off
	global_load_dwordx4 v[90:93], v[88:89], off offset:-2048
	global_load_dwordx4 v[98:101], v[8:9], off
	global_load_dwordx4 v[102:105], v[8:9], off offset:16
	s_or_b64 exec, exec, s[20:21]
	v_lshlrev_b64 v[4:5], 12, v[4:5]
	v_add_u32_e32 v20, s46, v20
	s_mov_b32 s4, 0xfffff
	v_lshl_add_u64 v[4:5], s[36:37], 0, v[4:5]
	v_cmp_lt_i32_e32 vcc, s4, v20
	v_lshl_add_u64 v[4:5], v[4:5], 0, v[96:97]
	v_add_u32_e32 v21, s47, v21
	s_or_b64 s[40:41], vcc, s[40:41]
	s_waitcnt vmcnt(0)
	v_cmp_lt_u32_e32 vcc, 1, v18
	s_and_saveexec_b64 s[10:11], vcc
	v_lshlrev_b32_e32 v106, 16, v84
	v_and_b32_e32 v107, 0xffff0000, v84
	v_lshlrev_b32_e32 v108, 16, v90
	v_and_b32_e32 v109, 0xffff0000, v90
	v_pk_mul_f32 v[110:111], v[106:107], v[108:109]
	v_pk_fma_f32 v[16:17], v[98:99], v[110:111], v[16:17]
	v_lshlrev_b32_e32 v106, 16, v85
	v_and_b32_e32 v107, 0xffff0000, v85
	v_lshlrev_b32_e32 v108, 16, v91
	v_and_b32_e32 v109, 0xffff0000, v91
	v_pk_mul_f32 v[110:111], v[106:107], v[108:109]
	v_pk_fma_f32 v[14:15], v[100:101], v[110:111], v[14:15]
	v_lshlrev_b32_e32 v106, 16, v86
	v_and_b32_e32 v107, 0xffff0000, v86
	v_lshlrev_b32_e32 v108, 16, v92
	v_and_b32_e32 v109, 0xffff0000, v92
	v_pk_mul_f32 v[110:111], v[106:107], v[108:109]
	v_pk_fma_f32 v[12:13], v[102:103], v[110:111], v[12:13]
	v_lshlrev_b32_e32 v106, 16, v87
	v_and_b32_e32 v107, 0xffff0000, v87
	v_lshlrev_b32_e32 v108, 16, v93
	v_and_b32_e32 v109, 0xffff0000, v93
	v_pk_mul_f32 v[110:111], v[106:107], v[108:109]
	v_pk_fma_f32 v[10:11], v[104:105], v[110:111], v[10:11]
	s_or_b64 exec, exec, s[10:11]
	v_cmp_ne_u32_e32 vcc, 0, v18
	s_and_saveexec_b64 s[10:11], vcc
	v_lshlrev_b32_e32 v106, 16, v64
	v_and_b32_e32 v107, 0xffff0000, v64
	v_lshlrev_b32_e32 v108, 16, v68
	v_and_b32_e32 v109, 0xffff0000, v68
	v_pk_mul_f32 v[110:111], v[106:107], v[108:109]
	v_pk_fma_f32 v[16:17], v[74:75], v[110:111], v[16:17]
	v_lshlrev_b32_e32 v106, 16, v65
	v_and_b32_e32 v107, 0xffff0000, v65
	v_lshlrev_b32_e32 v108, 16, v69
	v_and_b32_e32 v109, 0xffff0000, v69
	v_pk_mul_f32 v[110:111], v[106:107], v[108:109]
	v_pk_fma_f32 v[14:15], v[76:77], v[110:111], v[14:15]
	v_lshlrev_b32_e32 v106, 16, v66
	v_and_b32_e32 v107, 0xffff0000, v66
	v_lshlrev_b32_e32 v108, 16, v70
	v_and_b32_e32 v109, 0xffff0000, v70
	v_pk_mul_f32 v[110:111], v[106:107], v[108:109]
	v_pk_fma_f32 v[12:13], v[78:79], v[110:111], v[12:13]
	v_lshlrev_b32_e32 v106, 16, v67
	v_and_b32_e32 v107, 0xffff0000, v67
	v_lshlrev_b32_e32 v108, 16, v71
	v_and_b32_e32 v109, 0xffff0000, v71
	v_pk_mul_f32 v[110:111], v[106:107], v[108:109]
	v_pk_fma_f32 v[10:11], v[80:81], v[110:111], v[10:11]
	s_or_b64 exec, exec, s[10:11]
	v_lshlrev_b32_e32 v106, 16, v46
	v_and_b32_e32 v107, 0xffff0000, v46
	v_lshlrev_b32_e32 v108, 16, v50
	v_and_b32_e32 v109, 0xffff0000, v50
	v_pk_mul_f32 v[110:111], v[106:107], v[108:109]
	v_pk_fma_f32 v[16:17], v[56:57], v[110:111], v[16:17]
	v_lshlrev_b32_e32 v106, 16, v47
	v_and_b32_e32 v107, 0xffff0000, v47
	v_lshlrev_b32_e32 v108, 16, v51
	v_and_b32_e32 v109, 0xffff0000, v51
	v_pk_mul_f32 v[110:111], v[106:107], v[108:109]
	v_pk_fma_f32 v[14:15], v[58:59], v[110:111], v[14:15]
	v_lshlrev_b32_e32 v106, 16, v48
	v_and_b32_e32 v107, 0xffff0000, v48
	v_lshlrev_b32_e32 v108, 16, v52
	v_and_b32_e32 v109, 0xffff0000, v52
	v_pk_mul_f32 v[110:111], v[106:107], v[108:109]
	v_pk_fma_f32 v[12:13], v[60:61], v[110:111], v[12:13]
	v_lshlrev_b32_e32 v106, 16, v49
	v_and_b32_e32 v107, 0xffff0000, v49
	v_lshlrev_b32_e32 v108, 16, v53
	v_and_b32_e32 v109, 0xffff0000, v53
	v_pk_mul_f32 v[110:111], v[106:107], v[108:109]
	v_pk_fma_f32 v[10:11], v[62:63], v[110:111], v[10:11]
	v_lshlrev_b32_e32 v106, 16, v40
	v_and_b32_e32 v107, 0xffff0000, v40
	v_pk_mul_f32 v[16:17], v[16:17], v[106:107]
	v_lshlrev_b32_e32 v106, 16, v41
	v_and_b32_e32 v107, 0xffff0000, v41
	v_pk_mul_f32 v[14:15], v[14:15], v[106:107]
	v_lshlrev_b32_e32 v106, 16, v42
	v_and_b32_e32 v107, 0xffff0000, v42
	v_pk_mul_f32 v[12:13], v[12:13], v[106:107]
	v_lshlrev_b32_e32 v106, 16, v43
	v_and_b32_e32 v107, 0xffff0000, v43
	v_pk_mul_f32 v[10:11], v[10:11], v[106:107]
	v_cvt_pk_bf16_f32 v0, v16, v17
	v_cvt_pk_bf16_f32 v1, v14, v15
	v_cvt_pk_bf16_f32 v2, v12, v13
	v_cvt_pk_bf16_f32 v3, v10, v11
	global_store_dwordx4 v[4:5], v[0:3], off offset:2048
	s_andn2_b64 exec, exec, s[40:41]
	s_cbranch_execnz .LBB0_141
